# SB unit prologue K/V tile loads hoisted above Q wait; route preamble x4 load issued with the dword loads; RG item setup conv_w/conv_b loads batched with deferred LDS writes
# baseline (speedup 1.0000x reference)
; __device__ __forceinline__ void phase_expert(CArgs& A, int l, unsigned char* lds, int tid, bool dry = false) {
;     ...
;     for (int i = tid; i < 1024; i += NTHREADS) { lg[i] = A.in[26][(size_t)l * DM + i]; lb[i] = A.in[27][(size_t)l * DM + i];
;         if (l < DEPTH - 1) *(f32x4*)(lw + 4 * i + 4 * (i >> 3)) = *(const f32x4*)(A.in[2] + (size_t)(l + 1) * 1024 * NIN + (size_t)i * NIN + 1280); }
.LBB0_35:
	global_load_dword v10, v[6:7], off
	global_load_dword v11, v[4:5], off
	s_andn2_b64 vcc, exec, s[10:11]
	s_cbranch_vccnz .Lrt_nox4
	global_load_dwordx4 v[16:19], v[2:3], off
	v_lshlrev_b32_e32 v14, 1, v9
	v_and_b32_e32 v14, -16, v14
	v_add_u32_e32 v14, v1, v14
	s_waitcnt vmcnt(1)
	ds_write2st64_b32 v8, v10, v11 offset1:16
	s_waitcnt vmcnt(0)
	ds_write_b128 v14, v[16:19]
	s_branch .LBB0_34
.Lrt_nox4:
	s_waitcnt vmcnt(0)
	ds_write2st64_b32 v8, v10, v11 offset1:16
	s_branch .LBB0_34

; __device__ __forceinline__ u32x4 pack8(const float* f) { u32x4 o; o.x = pk2(f[0], f[1]); o.y = pk2(f[2], f[3]); o.z = pk2(f[4], f[5]); o.w = pk2(f[6], f[7]); return o; }
; template <int MODE>
; __device__ __forceinline__ void attn_unit(const bf16* P, bf16* Y, int b, int h, int qb, unsigned char* lds, int tid) {
;     ...
;     bf16x8 qf[4];
; #pragma unroll
;     for (int ks = 0; ks < 4; ++ks) { float f[8]; unpack8(*(const u32x4*)(P + rowq * NP + qcol + 16 * ks + 8 * hf), f);
; #pragma unroll
;         for (int i = 0; i < 8; ++i) f[i] *= 0.125f * LOG2E;
;         qf[ks] = __builtin_bit_cast(bf16x8, pack8(f)); }
;     ...
;     u32x4 kreg[2], vreg[2];
;     { const int st0 = (MODE == 0) ? 0 : (nsup - 1);
; #pragma unroll
;       for (int j = 0; j < 2; ++j) { const size_t kr = ((size_t)b * SEQ + st0 * 128 + 64 * j + skey) * NP;
;           kreg[j] = *(const u32x4*)(P + kr + kcol + sdc); vreg[j] = *(const u32x4*)(P + kr + vcol + sdc); } }
.LBB0_246:
	s_xor_b64 s[36:37], s[42:43], -1
	s_and_b64 s[0:1], s[42:43], exec
	s_cselect_b32 s0, s8, s41
	v_lshl_add_u32 v144, s0, 8, v143
	v_or_b32_e32 v146, v144, v119
	v_ashrrev_i32_e32 v147, 31, v146
	v_lshl_add_u64 v[2:3], s[4:5], 0, v[146:147]
	v_mad_u64_u32 v[14:15], s[42:43], v2, s79, v[126:127]
	v_mad_i32_i24 v15, v3, s79, v15
	global_load_dwordx4 v[2:5], v[14:15], off offset:2560
	global_load_dwordx4 v[6:9], v[14:15], off offset:2592
	global_load_dwordx4 v[10:13], v[14:15], off offset:2624
	s_nop 0
	global_load_dwordx4 v[14:17], v[14:15], off offset:2656
	s_lshl_b32 s9, s0, 1
	s_or_b32 s50, s9, 1
	s_lshl_b32 s0, s50, 7
	s_mov_b32 s1, s15
	v_lshl_add_u64 v[210:211], v[120:121], 0, s[0:1]
	v_mad_u64_u32 v[212:213], s[98:99], v210, s79, v[128:129]
	v_mad_i32_i24 v213, v211, s79, v213
	global_load_dwordx4 v[94:97], v[212:213], off offset:3072
	global_load_dwordx4 v[98:101], v[212:213], off offset:3584
	s_or_b32 s100, s0, 64
	s_mov_b32 s101, s15
	v_lshl_add_u64 v[210:211], v[120:121], 0, s[100:101]
	v_mad_u64_u32 v[212:213], s[98:99], v210, s79, v[128:129]
	v_mad_i32_i24 v213, v211, s79, v213
	global_load_dwordx4 v[106:109], v[212:213], off offset:3072
	global_load_dwordx4 v[110:113], v[212:213], off offset:3584
	s_add_i32 s51, s9, 2
	v_mov_b32_e32 v148, 0
	s_waitcnt vmcnt(4)
	v_lshlrev_b32_e32 v21, 16, v5
	s_waitcnt vmcnt(4)
	v_lshlrev_b32_e32 v23, 16, v7
	v_lshlrev_b32_e32 v22, 16, v6
	v_lshlrev_b32_e32 v20, 16, v4
	v_and_b32_e32 v5, 0xffff0000, v5
	v_and_b32_e32 v4, 0xffff0000, v4
	v_and_b32_e32 v7, 0xffff0000, v7
	v_and_b32_e32 v6, 0xffff0000, v6
	v_lshlrev_b32_e32 v25, 16, v9
	v_lshlrev_b32_e32 v24, 16, v8
	v_pk_mul_f32 v[22:23], v[22:23], s[26:27] op_sel_hi:[1,0]
	v_and_b32_e32 v9, 0xffff0000, v9
	v_and_b32_e32 v8, 0xffff0000, v8
	v_pk_mul_f32 v[20:21], v[20:21], s[26:27] op_sel_hi:[1,0]
	v_pk_mul_f32 v[4:5], v[4:5], s[26:27] op_sel_hi:[1,0]
	v_pk_mul_f32 v[6:7], v[6:7], s[26:27] op_sel_hi:[1,0]
	v_pk_mul_f32 v[24:25], v[24:25], s[26:27] op_sel_hi:[1,0]
	v_bfe_u32 v41, v22, 16, 1
	v_bfe_u32 v42, v23, 16, 1
	v_pk_mul_f32 v[8:9], v[8:9], s[26:27] op_sel_hi:[1,0]
	v_bfe_u32 v1, v5, 16, 1
	v_bfe_u32 v36, v21, 16, 1
	v_bfe_u32 v39, v7, 16, 1
	v_bfe_u32 v40, v6, 16, 1
	v_bfe_u32 v43, v24, 16, 1
	v_bfe_u32 v44, v25, 16, 1
	v_add3_u32 v23, v23, v42, s84
	v_add3_u32 v22, v22, v41, s84
	v_bfe_u32 v37, v9, 16, 1
	v_bfe_u32 v38, v8, 16, 1
	v_add3_u32 v1, v5, v1, s84
	v_add3_u32 v5, v21, v36, s84
	v_add3_u32 v6, v6, v40, s84
	v_add3_u32 v7, v7, v39, s84
	v_add3_u32 v21, v25, v44, s84
	v_add3_u32 v24, v24, v43, s84
	v_lshrrev_b32_e32 v22, 16, v22
	v_lshrrev_b32_e32 v23, 16, v23
	v_add3_u32 v8, v8, v38, s84
	v_add3_u32 v9, v9, v37, s84
	v_lshrrev_b32_e32 v24, 16, v24
	v_lshrrev_b32_e32 v21, 16, v21
	v_and_or_b32 v91, v7, s3, v23
	v_and_or_b32 v90, v6, s3, v22
	v_lshl_add_u64 v[6:7], v[120:121], 0, s[0:1]
	v_and_or_b32 v93, v9, s3, v21
	v_and_or_b32 v92, v8, s3, v24
	v_mad_u64_u32 v[8:9], s[42:43], v6, s79, v[128:129]
	s_or_b32 s0, s0, 64
	v_mad_i32_i24 v9, v7, s79, v9
	v_lshl_add_u64 v[6:7], v[120:121], 0, s[0:1]
	v_mad_u64_u32 v[8:9], s[0:1], v6, s79, v[128:129]
	v_mad_i32_i24 v9, v7, s79, v9
	v_lshlrev_b32_e32 v19, 16, v3
	v_lshlrev_b32_e32 v18, 16, v2
	v_and_b32_e32 v3, 0xffff0000, v3
	v_and_b32_e32 v2, 0xffff0000, v2
	v_pk_mul_f32 v[18:19], v[18:19], s[26:27] op_sel_hi:[1,0]
	v_bfe_u32 v35, v20, 16, 1
	v_pk_mul_f32 v[2:3], v[2:3], s[26:27] op_sel_hi:[1,0]
	v_bfe_u32 v30, v4, 16, 1
	v_bfe_u32 v33, v18, 16, 1
	v_bfe_u32 v34, v19, 16, 1
	v_add3_u32 v20, v20, v35, s84
	s_waitcnt vmcnt(5)
; __device__ __forceinline__ u32x4 pack8(const float* f) { u32x4 o; o.x = pk2(f[0], f[1]); o.y = pk2(f[2], f[3]); o.z = pk2(f[4], f[5]); o.w = pk2(f[6], f[7]); return o; }
; template <int MODE>
; __device__ __forceinline__ void attn_unit(const bf16* P, bf16* Y, int b, int h, int qb, unsigned char* lds, int tid) {
;     ...
;     for (int ks = 0; ks < 4; ++ks) { float f[8]; unpack8(*(const u32x4*)(P + rowq * NP + qcol + 16 * ks + 8 * hf), f);
; #pragma unroll
;         for (int i = 0; i < 8; ++i) f[i] *= 0.125f * LOG2E;
;         qf[ks] = __builtin_bit_cast(bf16x8, pack8(f)); }
;     f32x16 o0, o1;
; #pragma unroll
;     for (int i = 0; i < 16; ++i) { o0[i] = 0.f; o1[i] = 0.f; }
	v_lshlrev_b32_e32 v29, 16, v13
	v_lshlrev_b32_e32 v28, 16, v12
	v_and_b32_e32 v13, 0xffff0000, v13
	v_bfe_u32 v31, v3, 16, 1
	v_bfe_u32 v32, v2, 16, 1
	v_add3_u32 v4, v4, v30, s84
	v_add3_u32 v19, v19, v34, s84
	v_add3_u32 v18, v18, v33, s84
	v_lshrrev_b32_e32 v20, 16, v20
	v_lshrrev_b32_e32 v5, 16, v5
	v_and_b32_e32 v12, 0xffff0000, v12
	v_lshlrev_b32_e32 v27, 16, v11
	v_lshlrev_b32_e32 v26, 16, v10
	v_and_b32_e32 v11, 0xffff0000, v11
	v_and_b32_e32 v10, 0xffff0000, v10
	v_add3_u32 v2, v2, v32, s84
	v_add3_u32 v3, v3, v31, s84
	v_lshrrev_b32_e32 v18, 16, v18
	v_lshrrev_b32_e32 v19, 16, v19
	v_and_or_b32 v89, v1, s3, v5
	v_and_or_b32 v88, v4, s3, v20
	v_pk_mul_f32 v[4:5], v[12:13], s[26:27] op_sel_hi:[1,0]
	v_pk_mul_f32 v[26:27], v[26:27], s[26:27] op_sel_hi:[1,0]
	v_pk_mul_f32 v[10:11], v[10:11], s[26:27] op_sel_hi:[1,0]
	v_and_or_b32 v87, v3, s3, v19
	v_and_or_b32 v86, v2, s3, v18
	v_pk_mul_f32 v[2:3], v[28:29], s[26:27] op_sel_hi:[1,0]
	v_bfe_u32 v1, v5, 16, 1
	v_bfe_u32 v6, v4, 16, 1
	v_bfe_u32 v8, v10, 16, 1
	v_add3_u32 v1, v5, v1, s84
	v_bfe_u32 v5, v26, 16, 1
	v_bfe_u32 v9, v2, 16, 1
	v_add3_u32 v8, v10, v8, s84
	v_add3_u32 v4, v4, v6, s84
	v_bfe_u32 v6, v27, 16, 1
	v_bfe_u32 v10, v3, 16, 1
	v_add3_u32 v2, v2, v9, s84
	v_add3_u32 v5, v26, v5, s84
	v_bfe_u32 v7, v11, 16, 1
	v_add3_u32 v3, v3, v10, s84
	v_add3_u32 v6, v27, v6, s84
	v_lshrrev_b32_e32 v5, 16, v5
	v_lshrrev_b32_e32 v2, 16, v2
	v_add3_u32 v7, v11, v7, s84
	v_lshrrev_b32_e32 v6, 16, v6
	v_lshrrev_b32_e32 v3, 16, v3
	v_and_or_b32 v104, v4, s3, v2
	v_and_or_b32 v102, v8, s3, v5
	s_waitcnt vmcnt(4)
	v_and_b32_e32 v5, 0xffff0000, v15
	v_and_b32_e32 v4, 0xffff0000, v14
	v_and_b32_e32 v9, 0xffff0000, v17
	v_and_b32_e32 v8, 0xffff0000, v16
	v_and_or_b32 v105, v1, s3, v3
	v_and_or_b32 v103, v7, s3, v6
	v_lshlrev_b32_e32 v3, 16, v15
	v_lshlrev_b32_e32 v2, 16, v14
	v_pk_mul_f32 v[4:5], v[4:5], s[26:27] op_sel_hi:[1,0]
	v_lshlrev_b32_e32 v7, 16, v17
	v_lshlrev_b32_e32 v6, 16, v16
	v_pk_mul_f32 v[8:9], v[8:9], s[26:27] op_sel_hi:[1,0]
	v_pk_mul_f32 v[2:3], v[2:3], s[26:27] op_sel_hi:[1,0]
	v_pk_mul_f32 v[6:7], v[6:7], s[26:27] op_sel_hi:[1,0]
	v_bfe_u32 v1, v9, 16, 1
	v_bfe_u32 v10, v8, 16, 1
	v_bfe_u32 v11, v5, 16, 1
	v_bfe_u32 v12, v4, 16, 1
	v_add3_u32 v4, v4, v12, s84
	v_add3_u32 v5, v5, v11, s84
	v_add3_u32 v8, v8, v10, s84
	v_add3_u32 v1, v9, v1, s84
	v_bfe_u32 v9, v2, 16, 1
	v_bfe_u32 v10, v3, 16, 1
	v_bfe_u32 v11, v6, 16, 1
	v_bfe_u32 v12, v7, 16, 1
	v_add3_u32 v7, v7, v12, s84
	v_add3_u32 v6, v6, v11, s84
	v_add3_u32 v3, v3, v10, s84
	v_add3_u32 v2, v2, v9, s84
	v_lshrrev_b32_e32 v2, 16, v2
	v_lshrrev_b32_e32 v3, 16, v3
	v_lshrrev_b32_e32 v6, 16, v6
	v_lshrrev_b32_e32 v7, 16, v7
	v_mov_b32_e32 v14, v0
	v_mov_b32_e32 v15, v0
	v_and_or_b32 v117, v1, s3, v7
	v_and_or_b32 v116, v8, s3, v6
	v_and_or_b32 v115, v5, s3, v3
	v_and_or_b32 v114, v4, s3, v2
	v_mov_b32_e32 v1, v0
	v_mov_b32_e32 v2, v0
	v_mov_b32_e32 v3, v0
	v_mov_b32_e32 v4, v0
	v_mov_b32_e32 v5, v0
	v_mov_b32_e32 v6, v0
	v_mov_b32_e32 v7, v0
	v_mov_b32_e32 v8, v0
	v_mov_b32_e32 v9, v0
	v_mov_b32_e32 v10, v0
	v_mov_b32_e32 v11, v0
	v_mov_b32_e32 v12, v0
	v_mov_b32_e32 v13, v0
	v_mov_b64_e32 v[32:33], v[14:15]
	v_mov_b64_e32 v[30:31], v[12:13]
	v_mov_b64_e32 v[28:29], v[10:11]
	v_mov_b64_e32 v[26:27], v[8:9]
	v_mov_b64_e32 v[24:25], v[6:7]
	v_mov_b64_e32 v[22:23], v[4:5]
	v_mov_b64_e32 v[20:21], v[2:3]
	v_mov_b64_e32 v[18:19], v[0:1]
	v_mov_b64_e32 v[16:17], v[14:15]
	s_mov_b32 s1, 0
	v_mov_b64_e32 v[14:15], v[12:13]
	v_mov_b64_e32 v[12:13], v[10:11]
	v_mov_b64_e32 v[10:11], v[8:9]
	v_mov_b64_e32 v[8:9], v[6:7]
	v_mov_b64_e32 v[6:7], v[4:5]
	v_mov_b64_e32 v[4:5], v[2:3]
	v_mov_b64_e32 v[2:3], v[0:1]

; __device__ __forceinline__ void rg_item(CArgs& A, int l, const bf16* P, bf16* Y, int b, int h, int cg, float* ldsf, int tid) {
;     ...
;     __syncthreads();
;     if (tid < 256) cw_s[tid] = conv_w[(tid >> 6) * 256 + (tid & 63)];
;     if (tid < 64) cb_s[tid] = conv_b[tid];
.LBB0_260:
	s_bfe_u32 s8, s9, 0x20002
	s_movk_i32 s1, 0x100
	s_lshl_b32 s0, s8, 6
	v_ashrrev_i32_e32 v2, 6, v118
	v_and_b32_e32 v3, 63, v118
	v_cmp_gt_i32_e32 vcc, s1, v118
	v_lshl_add_u32 v1, v118, 2, 0
	s_barrier
	s_and_saveexec_b64 s[4:5], vcc
	s_cbranch_execz .LBB0_262
	s_lshl_b32 s1, s0, 2
	s_add_u32 s10, s74, s1
	v_lshl_or_b32 v4, v2, 8, v3
	s_addc_u32 s11, s75, 0
	v_ashrrev_i32_e32 v5, 31, v4
	v_lshl_add_u64 v[4:5], v[4:5], 2, s[10:11]
	global_load_dword v210, v[4:5], off
.LBB0_262:
	s_or_b64 exec, exec, s[4:5]
	v_cmp_gt_i32_e32 vcc, 64, v118
	v_ashrrev_i32_e32 v119, 31, v118
	s_and_saveexec_b64 s[4:5], vcc
	s_cbranch_execz .LBB0_264
	s_lshl_b32 s1, s0, 2
	s_add_u32 s10, s36, s1
	s_addc_u32 s11, s37, 0
	v_lshl_add_u64 v[4:5], v[118:119], 2, s[10:11]
	global_load_dword v211, v[4:5], off

; __device__ __forceinline__ u32x4 pack8(const float* f) { u32x4 o; o.x = pk2(f[0], f[1]); o.y = pk2(f[2], f[3]); o.z = pk2(f[4], f[5]); o.w = pk2(f[6], f[7]); return o; }
; __device__ __forceinline__ void rg_item(CArgs& A, int l, const bf16* P, bf16* Y, int b, int h, int cg, float* ldsf, int tid) {
;     ...
;     if (tid < 256) cw_s[tid] = conv_w[(tid >> 6) * 256 + (tid & 63)];
;     if (tid < 64) cb_s[tid] = conv_b[tid];
;     ...
;     bf16x8 wfrag[4];
;     { const int n = r, hfn = (n >> 2) & 1, idx = (n & 3) + 4 * (n >> 3), gsel = idx >> 3, ch = cg * 16 + 8 * hfn + (idx & 7);
;       const float* wsrc = gsel ? wi : wa;
; #pragma unroll
;       for (int ks = 0; ks < 4; ++ks) { float f[8];
; #pragma unroll
;           for (int j = 0; j < 8; ++j) f[j] = wsrc[(16 * ks + 8 * hf + j) * 64 + ch];
;           wfrag[ks] = __builtin_bit_cast(bf16x8, pack8(f)); } }
.LBB0_266:
	s_or_b64 exec, exec, s[4:5]
	v_lshrrev_b32_e32 v5, 1, v118
	v_lshlrev_b32_e32 v6, 1, v118
	v_and_b32_e32 v4, 3, v118
	v_and_b32_e32 v6, 8, v6
	v_and_b32_e32 v5, 4, v5
	v_or3_b32 v8, v5, v4, v6
	v_and_b32_e32 v4, 16, v118
	v_mov_b32_e32 v5, s61
	v_mov_b32_e32 v6, s57
	v_cmp_eq_u32_e32 vcc, 0, v4
	v_lshrrev_b32_e32 v14, 5, v3
	v_mov_b32_e32 v4, s60
	v_cndmask_b32_e32 v5, v5, v6, vcc
	v_mov_b32_e32 v6, s56
	v_cndmask_b32_e32 v4, v4, v6, vcc
	v_lshlrev_b32_e32 v9, 9, v14
	v_lshl_add_u64 v[4:5], v[4:5], 0, s[52:53]
	s_lshl_b32 s14, s8, 14
	v_or3_b32 v6, s1, v9, v8
	v_lshl_add_u64 v[4:5], v[4:5], 0, s[14:15]
	v_lshlrev_b32_e32 v6, 2, v6
	v_mov_b32_e32 v7, v0
	v_lshl_add_u64 v[6:7], v[4:5], 0, v[6:7]
	v_or3_b32 v8, v9, v8, s1
	global_load_dword v15, v[6:7], off
	v_lshlrev_b32_e32 v12, 2, v8
	v_or_b32_e32 v8, 0x100, v12
	v_mov_b32_e32 v9, v0
	v_lshl_add_u64 v[8:9], v[4:5], 0, v[8:9]
	v_or_b32_e32 v10, 0x200, v12
	v_mov_b32_e32 v11, v0
	v_lshl_add_u64 v[10:11], v[4:5], 0, v[10:11]
	global_load_dword v16, v[8:9], off
	global_load_dword v17, v[10:11], off
	v_or_b32_e32 v8, 0x300, v12
	v_mov_b32_e32 v9, v0
	v_lshl_add_u64 v[8:9], v[4:5], 0, v[8:9]
	v_or_b32_e32 v10, 0x400, v12
	v_mov_b32_e32 v11, v0
	v_lshl_add_u64 v[10:11], v[4:5], 0, v[10:11]
	global_load_dword v19, v[8:9], off
	global_load_dword v20, v[10:11], off
	v_or_b32_e32 v8, 0x500, v12
	v_mov_b32_e32 v9, v0
	v_or_b32_e32 v10, 0x600, v12
	v_mov_b32_e32 v11, v0
	v_lshl_add_u64 v[8:9], v[4:5], 0, v[8:9]
	v_lshl_add_u64 v[10:11], v[4:5], 0, v[10:11]
	v_or_b32_e32 v12, 0x700, v12
	v_mov_b32_e32 v13, v0
	v_lshl_add_u64 v[4:5], v[4:5], 0, v[12:13]
	global_load_dword v12, v[8:9], off
	s_nop 0
	global_load_dword v10, v[10:11], off
	s_nop 0
	global_load_dword v11, v[4:5], off
	v_add_co_u32_e32 v4, vcc, s33, v6
	s_movk_i32 s5, 0x3000
	s_nop 0
	v_addc_co_u32_e32 v5, vcc, 0, v7, vcc
	global_load_dword v13, v[4:5], off offset:-4096
	v_add_co_u32_e32 v8, vcc, s85, v6
	s_ashr_i32 s4, s9, 4
	s_nop 0
	v_addc_co_u32_e32 v9, vcc, 0, v7, vcc
	global_load_dword v22, v[8:9], off offset:256
	global_load_dword v23, v[8:9], off offset:512
	global_load_dword v24, v[8:9], off offset:768
	global_load_dword v25, v[8:9], off offset:1024
	global_load_dword v26, v[8:9], off offset:1280
	global_load_dword v27, v[8:9], off offset:1536
	s_nop 0
	global_load_dword v8, v[8:9], off offset:1792
	s_nop 0
	global_load_dword v9, v[4:5], off
	global_load_dword v28, v[4:5], off offset:256
	global_load_dword v29, v[4:5], off offset:512
	global_load_dword v30, v[4:5], off offset:768
	global_load_dword v31, v[4:5], off offset:1024
	global_load_dword v32, v[4:5], off offset:1280
	global_load_dword v33, v[4:5], off offset:1536
	global_load_dword v35, v[4:5], off offset:1792
	v_add_co_u32_e32 v4, vcc, s5, v6
	s_movk_i32 s5, 0x13b0
	s_nop 0
	v_addc_co_u32_e32 v5, vcc, 0, v7, vcc
	global_load_dword v6, v[4:5], off
	global_load_dword v36, v[4:5], off offset:512
	global_load_dword v37, v[4:5], off offset:1280
	s_lshl_b32 s54, s0, 1
	s_add_u32 s10, s38, s54
	s_addc_u32 s11, s39, 0
	v_and_b32_e32 v34, 31, v118
	v_ashrrev_i32_e32 v88, 4, v118
	v_cmp_gt_i32_e64 s[40:41], 16, v2
	s_waitcnt vmcnt(0)
	v_cmp_gt_i32_e32 vcc, 0x100, v118
	s_and_saveexec_b64 s[98:99], vcc
	ds_write_b32 v1, v210
	s_or_b64 exec, exec, s[98:99]
	v_cmp_gt_i32_e32 vcc, 64, v118
	s_and_saveexec_b64 s[98:99], vcc
	ds_write_b32 v1, v211 offset:1024
	s_or_b64 exec, exec, s[98:99]
	v_add_u32_e32 v93, -8, v2
	s_mov_b32 s87, 0
	v_cmp_lt_i32_e64 s[42:43], 0, v88
	v_cmp_eq_u32_e64 s[44:45], 31, v88
	s_waitcnt vmcnt(26)
	v_bfe_u32 v7, v15, 16, 1
	v_add3_u32 v7, v15, v7, s84
	global_load_dword v15, v[4:5], off offset:256
	v_lshrrev_b32_e32 v7, 16, v7
	s_waitcnt vmcnt(26)
	v_bfe_u32 v18, v16, 16, 1
	v_add3_u32 v16, v16, v18, s84
	v_and_or_b32 v18, v16, s3, v7
	global_load_dword v7, v[4:5], off offset:768
	s_waitcnt vmcnt(26)
	v_bfe_u32 v16, v17, 16, 1
	v_add3_u32 v16, v17, v16, s84
	global_load_dword v17, v[4:5], off offset:1024
	s_waitcnt vmcnt(26)
	v_bfe_u32 v21, v19, 16, 1
	v_lshrrev_b32_e32 v16, 16, v16
	v_add3_u32 v19, v19, v21, s84
	v_and_or_b32 v19, v19, s3, v16
	global_load_dword v16, v[4:5], off offset:1536
	s_waitcnt vmcnt(26)
	v_bfe_u32 v21, v20, 16, 1
	global_load_dword v4, v[4:5], off offset:1792
	v_add3_u32 v20, v20, v21, s84
	v_lshrrev_b32_e32 v5, 16, v20
	s_waitcnt vmcnt(26)
; __device__ __forceinline__ u32x4 pack8(const float* f) { u32x4 o; o.x = pk2(f[0], f[1]); o.y = pk2(f[2], f[3]); o.z = pk2(f[4], f[5]); o.w = pk2(f[6], f[7]); return o; }
; __device__ __forceinline__ void rg_item(CArgs& A, int l, const bf16* P, bf16* Y, int b, int h, int cg, float* ldsf, int tid) {
;     ...
;     bf16x8 wfrag[4];
;     { const int n = r, hfn = (n >> 2) & 1, idx = (n & 3) + 4 * (n >> 3), gsel = idx >> 3, ch = cg * 16 + 8 * hfn + (idx & 7);
;       const float* wsrc = gsel ? wi : wa;
; #pragma unroll
;       for (int ks = 0; ks < 4; ++ks) { float f[8];
; #pragma unroll
;           for (int j = 0; j < 8; ++j) f[j] = wsrc[(16 * ks + 8 * hf + j) * 64 + ch];
;           wfrag[ks] = __builtin_bit_cast(bf16x8, pack8(f)); } }
;     __syncthreads();
;     const int c = tid & 15, seg = tid >> 4;
;     for (int qtr = 0; qtr < 4; ++qtr) {
; #pragma unroll 1
;         for (int tl = wave; tl < 16; tl += 8) {
;             const int tq = tl * 32 + r, t = qtr * 512 + tq;
;             unsigned char* xs = (unsigned char*)(u_s + 8192) + wave * 5040;
	v_bfe_u32 v20, v12, 16, 1
	v_add3_u32 v12, v12, v20, s84
	v_and_or_b32 v20, v12, s3, v5
	s_waitcnt vmcnt(25)
	v_bfe_u32 v5, v10, 16, 1
	v_add3_u32 v5, v10, v5, s84
	s_waitcnt vmcnt(24)
	v_bfe_u32 v10, v11, 16, 1
	v_lshrrev_b32_e32 v5, 16, v5
	v_add3_u32 v10, v11, v10, s84
	v_and_or_b32 v21, v10, s3, v5
	s_waitcnt vmcnt(23)
	v_bfe_u32 v5, v13, 16, 1
	v_add3_u32 v5, v13, v5, s84
	s_waitcnt vmcnt(22)
	v_bfe_u32 v10, v22, 16, 1
	v_lshrrev_b32_e32 v5, 16, v5
	v_add3_u32 v10, v22, v10, s84
	v_and_or_b32 v22, v10, s3, v5
	s_waitcnt vmcnt(21)
	v_bfe_u32 v5, v23, 16, 1
	v_add3_u32 v5, v23, v5, s84
	s_waitcnt vmcnt(20)
	v_bfe_u32 v10, v24, 16, 1
	v_lshrrev_b32_e32 v5, 16, v5
	v_add3_u32 v10, v24, v10, s84
	v_and_or_b32 v23, v10, s3, v5
	s_waitcnt vmcnt(19)
	v_bfe_u32 v5, v25, 16, 1
	v_add3_u32 v5, v25, v5, s84
	s_waitcnt vmcnt(18)
	v_bfe_u32 v10, v26, 16, 1
	v_lshrrev_b32_e32 v5, 16, v5
	v_add3_u32 v10, v26, v10, s84
	v_and_or_b32 v24, v10, s3, v5
	s_waitcnt vmcnt(17)
	v_bfe_u32 v5, v27, 16, 1
	v_add3_u32 v5, v27, v5, s84
	s_waitcnt vmcnt(16)
	v_bfe_u32 v10, v8, 16, 1
	v_lshrrev_b32_e32 v5, 16, v5
	v_add3_u32 v8, v8, v10, s84
	v_and_or_b32 v25, v8, s3, v5
	s_waitcnt vmcnt(15)
	v_bfe_u32 v5, v9, 16, 1
	v_add3_u32 v5, v9, v5, s84
	s_waitcnt vmcnt(14)
	v_bfe_u32 v8, v28, 16, 1
	v_lshrrev_b32_e32 v5, 16, v5
	v_add3_u32 v8, v28, v8, s84
	v_and_or_b32 v26, v8, s3, v5
	s_waitcnt vmcnt(13)
	v_bfe_u32 v5, v29, 16, 1
	v_add3_u32 v5, v29, v5, s84
	s_waitcnt vmcnt(12)
	v_bfe_u32 v8, v30, 16, 1
	v_lshrrev_b32_e32 v5, 16, v5
	v_add3_u32 v8, v30, v8, s84
	v_and_or_b32 v27, v8, s3, v5
	s_waitcnt vmcnt(11)
	v_bfe_u32 v5, v31, 16, 1
	v_add3_u32 v5, v31, v5, s84
	s_waitcnt vmcnt(10)
	v_bfe_u32 v8, v32, 16, 1
	v_lshrrev_b32_e32 v5, 16, v5
	v_add3_u32 v8, v32, v8, s84
	v_and_or_b32 v28, v8, s3, v5
	s_waitcnt vmcnt(9)
	v_bfe_u32 v5, v33, 16, 1
	v_add3_u32 v5, v33, v5, s84
	s_waitcnt vmcnt(8)
	v_bfe_u32 v8, v35, 16, 1
	v_lshrrev_b32_e32 v5, 16, v5
	v_add3_u32 v8, v35, v8, s84
	v_and_or_b32 v29, v8, s3, v5
	s_waitcnt vmcnt(7)
	v_bfe_u32 v5, v6, 16, 1
	v_add3_u32 v5, v6, v5, s84
	s_waitcnt vmcnt(4)
	v_bfe_u32 v6, v15, 16, 1
	v_lshrrev_b32_e32 v5, 16, v5
	v_add3_u32 v6, v15, v6, s84
	v_and_or_b32 v30, v6, s3, v5
	v_bfe_u32 v5, v36, 16, 1
	v_add3_u32 v5, v36, v5, s84
	v_lshrrev_b32_e32 v5, 16, v5
	v_lshlrev_b32_e32 v11, 4, v118
	s_waitcnt vmcnt(3)
	v_bfe_u32 v6, v7, 16, 1
	v_add3_u32 v6, v7, v6, s84
	v_and_or_b32 v31, v6, s3, v5
	s_waitcnt vmcnt(2)
	v_bfe_u32 v5, v17, 16, 1
	v_add3_u32 v5, v17, v5, s84
	v_bfe_u32 v6, v37, 16, 1
	v_lshrrev_b32_e32 v5, 16, v5
	v_add3_u32 v6, v37, v6, s84
	v_and_or_b32 v32, v6, s3, v5
	s_waitcnt vmcnt(1)
	v_bfe_u32 v5, v16, 16, 1
	v_add3_u32 v5, v16, v5, s84
	s_waitcnt vmcnt(0)
	v_bfe_u32 v6, v4, 16, 1
	v_lshrrev_b32_e32 v5, 16, v5
	v_add3_u32 v4, v4, v6, s84
	v_and_or_b32 v33, v4, s3, v5
	v_mul_lo_u32 v5, v2, s5
	v_readlane_b32 s5, v250, 9
	v_and_b32_e32 v6, 0x70, v11
	v_mov_b32_e32 v7, v0
	v_add_u32_e32 v5, s5, v5
	s_ashr_i32 s5, s4, 31
	v_and_b32_e32 v4, 15, v118
	s_lshl_b64 s[58:59], s[4:5], 11
	v_lshl_add_u64 v[78:79], s[10:11], 0, v[6:7]
	v_add_u32_e32 v12, v5, v6
	v_and_b32_e32 v6, -16, v118
	v_lshl_add_u32 v5, v14, 4, v5
	v_lshlrev_b32_e32 v14, 2, v4
	v_ashrrev_i32_e32 v7, 31, v6
	s_add_u32 s0, s6, s54
	v_lshl_add_u64 v[80:81], s[58:59], 0, v[6:7]
	s_addc_u32 s4, s7, 0
	s_lshl_b32 s62, s1, 1
	v_lshl_or_b32 v6, v6, 6, v14
	s_add_u32 s0, s0, s62
	v_add_u32_e32 v91, 0, v6
	v_or_b32_e32 v6, v11, v4
	s_addc_u32 s1, s4, 0
	v_lshlrev_b32_e32 v8, 1, v4
	v_mov_b32_e32 v9, v0
	v_lshl_or_b32 v6, v6, 2, v185
	v_lshrrev_b32_e32 v10, 3, v3
	v_and_b32_e32 v3, 32, v3
	v_lshl_add_u64 v[82:83], s[0:1], 0, v[8:9]
	v_add_u32_e32 v92, 0, v6
	v_lshlrev_b32_e32 v6, 11, v2
	v_lshlrev_b32_e32 v9, 6, v34
	v_add_u32_e32 v89, 0, v3
	v_or_b32_e32 v8, 32, v10
	v_or3_b32 v3, v6, v9, v3
	s_add_i32 s0, 0, 0x1600
	v_and_b32_e32 v13, 32, v118
	v_mul_u32_u24_e32 v7, 0x90, v10
	v_cmp_gt_u32_e64 s[46:47], 35, v8
	v_mul_u32_u24_e32 v8, 0x90, v34
	v_add_u32_e32 v94, s0, v3
	v_lshl_or_b32 v2, v2, 5, v10
	s_add_i32 s0, 0, 0x600
	v_add_u32_e32 v90, 0, v14
	v_add_u32_e32 v95, 29, v2
	v_add_u32_e32 v96, s0, v14
	v_add_u32_e32 v97, 0, v13
	v_add_u32_e32 v98, v5, v8
	v_lshlrev_b32_e32 v84, 1, v4
	v_add_u32_e32 v99, v12, v7
	s_waitcnt lgkmcnt(0)
	s_barrier
	s_branch .LBB0_268
